# MoE weight conversion: last 768 tiles moved from the attention phase to the end of the input-projection phase on the 128 workgroups that run 12 of 13 GEMM units there
# speedup vs baseline: 1.0049x; 1.0006x over previous
.LBB0_485:
	s_waitcnt vmcnt(0)
	v_readlane_b32 s38, v255, 19
	v_readlane_b32 s39, v255, 20
	s_barrier
	v_readlane_b32 s0, v255, 4
	s_add_i32 s1, s0, -64
	s_cmp_lt_u32 s1, 0x80
	s_cbranch_scc1 .LBB0_486
	s_add_i32 s1, s0, 0xffffff80
	s_cmp_lt_u32 s0, 64
	s_cselect_b32 s1, s0, s1
	v_writelane_b32 v255, s12, 56
	v_writelane_b32 v255, s13, 57
	s_nop 1
	v_readlane_b32 s2, v255, 3
	s_movk_i32 s3, 0x80
	s_mov_b32 s0, 2
	v_writelane_b32 v255, s2, 55
	v_writelane_b32 v255, s3, 3
	v_writelane_b32 v255, s0, 59
	s_add_i32 s96, s1, 0x5d00
	s_movk_i32 s101, 0x5fff
	s_branch .Lmy_c1
.Lmy_ph2t_ret:
	v_readlane_b32 s2, v255, 55
	s_mov_b32 s0, 0
	v_readlane_b32 s96, v255, 21
	v_readlane_b32 s12, v255, 56
	v_readlane_b32 s13, v255, 57
	v_writelane_b32 v255, s2, 3
	v_writelane_b32 v255, s0, 59
	s_nop 1
	v_readlane_b32 s38, v255, 19
	v_readlane_b32 s39, v255, 20

.LBB0_783:
	v_readlane_b32 s0, v255, 13
	v_readlane_b32 s1, v255, 14
	s_cmp_lt_i32 s0, 6
	s_cselect_b64 s[0:1], -1, 0
	s_and_b64 s[8:9], s[0:1], s[4:5]
	s_andn2_b64 vcc, exec, s[8:9]
	s_cbranch_vccnz .LBB0_929
	s_mov_b32 s0, 0
	v_writelane_b32 v255, s0, 59
	s_nop 1
	v_readlane_b32 s0, v255, 4
	s_bitcmp1_b32 s0, 0
	s_cselect_b64 s[10:11], -1, 0
	s_and_b64 vcc, exec, s[10:11]
	s_cbranch_vccnz .LBB0_824
	s_movk_i32 s101, 0x5cff
.Lmy_c1:
	s_cmp_gt_i32 s96, s101
	s_mov_b32 s1, 0
	s_cbranch_scc1 .LBB0_787
	v_readlane_b32 s2, v255, 3
	s_abs_i32 s0, s2
	v_cvt_f32_u32_e32 v1, s0
	s_sub_i32 s3, 0, s0
	s_sub_i32 s1, s101, s96
	s_ashr_i32 s2, s2, 31
	v_rcp_iflag_f32_e32 v1, v1
	s_nop 0
	v_mul_f32_e32 v1, 0x4f7ffffe, v1
	v_cvt_u32_f32_e32 v1, v1
	s_nop 0
	v_readfirstlane_b32 s4, v1
	s_mul_i32 s3, s3, s4
	s_mul_hi_u32 s3, s4, s3
	s_add_i32 s4, s4, s3
	s_mul_hi_u32 s3, s1, s4
	s_mul_i32 s4, s3, s0
	s_sub_i32 s1, s1, s4
	s_add_i32 s5, s3, 1
	s_sub_i32 s4, s1, s0
	s_cmp_ge_u32 s1, s0
	s_cselect_b32 s3, s5, s3
	s_cselect_b32 s1, s4, s1
	s_add_i32 s4, s3, 1
	s_cmp_ge_u32 s1, s0
	s_cselect_b32 s0, s4, s3
	s_xor_b32 s0, s0, s2
	s_sub_i32 s0, s0, s2
	s_add_i32 s1, s0, 1

.LBB0_824:
	v_readlane_b32 s0, v255, 59
	s_cmp_eq_u32 s0, 2
	s_cbranch_scc1 .Lmy_ph2t_ret
	s_cmpk_lt_i32 s96, 0x200
	s_cbranch_scc0 .LBB0_862
	s_load_dwordx2 s[6:7], s[38:39], 0xc0
	s_lshl_b32 s0, s96, 5
	s_and_b32 s14, s0, 0xfffff800
	s_ashr_i32 s15, s14, 31
	s_lshl_b64 s[4:5], s[14:15], 11
	s_and_b32 s0, s0, 0x780
	s_or_b32 s4, s4, s0
	s_waitcnt lgkmcnt(0)
	s_add_u32 s37, s6, 0xc000000
	s_addc_u32 s42, s7, 0
	s_lshl_b64 s[2:3], s[4:5], 1
	s_add_u32 s12, s37, s2
	s_addc_u32 s13, s42, s3
	s_lshl_b32 s0, s96, 8
	s_and_b32 s0, s0, 0x300
	s_lshl_b32 s1, s0, 11
	s_lshl_b32 s15, s0, 12
	s_add_u32 s12, s12, s15
	s_addc_u32 s13, s13, 0
	s_add_u32 s43, s6, 0x24000000
	s_addc_u32 s44, s7, 0
	s_add_u32 s66, s43, s2
	s_addc_u32 s67, s44, s3
	s_add_u32 s45, s6, 0x28000000
	s_addc_u32 s47, s7, 0
	s_add_u32 s68, s45, s2
	v_readfirstlane_b32 s2, v0
	s_addc_u32 s69, s47, s3
	s_lshr_b32 s2, s2, 6
	v_and_b32_e32 v205, 31, v0
	v_lshrrev_b32_e32 v1, 1, v0
	s_lshl_b32 s3, s2, 17
	v_lshlrev_b32_e32 v12, 12, v205
	v_and_b32_e32 v17, 16, v1
	v_or3_b32 v1, s3, v12, v17
	global_load_dwordx4 v[158:161], v1, s[12:13]
	global_load_dwordx4 v[154:157], v1, s[12:13] offset:32
	global_load_dwordx4 v[150:153], v1, s[12:13] offset:64
	global_load_dwordx4 v[146:149], v1, s[12:13] offset:96
	global_load_dwordx4 v[142:145], v1, s[12:13] offset:128
	global_load_dwordx4 v[138:141], v1, s[12:13] offset:160
	global_load_dwordx4 v[134:137], v1, s[12:13] offset:192
	global_load_dwordx4 v[130:133], v1, s[12:13] offset:224
	v_lshlrev_b32_e32 v1, 4, v0
	v_lshrrev_b32_e32 v15, 4, v0
	v_and_b32_e32 v16, 0xf0, v1
	v_lshlrev_b32_e32 v13, 12, v15
	v_or_b32_e32 v10, v13, v16
	v_mov_b32_e32 v11, 0
	v_lshl_add_u64 v[2:3], s[68:69], 0, v[10:11]
	s_mov_b32 s3, 0x20000
	v_add_co_u32_e32 v18, vcc, s3, v2
	v_lshl_add_u64 v[6:7], s[66:67], 0, v[10:11]
	s_nop 0
	v_addc_co_u32_e32 v19, vcc, 0, v3, vcc
	v_add_co_u32_e32 v20, vcc, s3, v6
	global_load_dwordx4 v[98:101], v10, s[68:69]
	global_load_dwordx4 v[2:5], v10, s[66:67]
	v_addc_co_u32_e32 v21, vcc, 0, v7, vcc
	global_load_dwordx4 v[102:105], v[18:19], off
	global_load_dwordx4 v[6:9], v[20:21], off
	s_lshl_b32 s18, s2, 13
	s_lshr_b32 s2, s0, 6
	s_or_b32 s16, s14, s0
	s_add_i32 s2, s2, 7
	s_add_i32 s3, s18, 0
	s_ashr_i32 s17, s16, 31
	s_lshr_b32 s2, s2, 2
	s_add_i32 s3, s3, 0x10800
	s_lshl_b64 s[14:15], s[16:17], 8
	v_lshlrev_b32_e32 v14, 8, v205
	s_add_u32 s14, s6, s14
	v_or3_b32 v10, s18, v14, v17
	s_addc_u32 s15, s7, s15
	v_lshl_add_u64 v[10:11], s[14:15], 0, v[10:11]
	s_mov_b64 s[14:15], 0x1800000
	v_lshl_add_u64 v[10:11], v[10:11], 0, s[14:15]

.LBB0_889:
	s_andn2_b64 vcc, exec, s[10:11]
	s_cbranch_vccnz .LBB0_929
	s_cmpk_gt_i32 s96, 0x5cff
	s_mov_b32 s1, 0
	s_waitcnt vmcnt(0) lgkmcnt(0)
	s_barrier
	s_cbranch_scc1 .LBB0_892
	v_readlane_b32 s2, v255, 3
	s_abs_i32 s0, s2
	v_cvt_f32_u32_e32 v1, s0
	s_sub_i32 s3, 0, s0
	s_sub_i32 s1, 0x5cff, s96
	s_ashr_i32 s2, s2, 31
	v_rcp_iflag_f32_e32 v1, v1
	s_nop 0
	v_mul_f32_e32 v1, 0x4f7ffffe, v1
	v_cvt_u32_f32_e32 v1, v1
	s_nop 0
	v_readfirstlane_b32 s4, v1
	s_mul_i32 s3, s3, s4
	s_mul_hi_u32 s3, s4, s3
	s_add_i32 s4, s4, s3
	s_mul_hi_u32 s3, s1, s4
	s_mul_i32 s4, s3, s0
	s_sub_i32 s1, s1, s4
	s_add_i32 s5, s3, 1
	s_sub_i32 s4, s1, s0
	s_cmp_ge_u32 s1, s0
	s_cselect_b32 s3, s5, s3
	s_cselect_b32 s1, s4, s1
	s_add_i32 s4, s3, 1
	s_cmp_ge_u32 s1, s0
	s_cselect_b32 s0, s4, s3
	s_xor_b32 s0, s0, s2
	s_sub_i32 s0, s0, s2
	s_add_i32 s1, s0, 1
